# instruction selection: sub-LN cross-lane sums by v_permlane16_swap + DPP row rotates instead of 80 ds_bpermute round trips per item (same additions, same order)
# speedup vs baseline: 1.0045x; 1.0006x over previous
; #define SBAR() __builtin_amdgcn_sched_barrier(0)
; template <int OFF> __device__ __forceinline__ s16x4 tr_read(int vb) { s16x4 r; asm volatile("ds_read_b64_tr_b16 %0, %1 offset:%2" : "=&v"(r) : "v"(vb), "i"(OFF) : "memory"); return r; }
; template <int D0> __device__ __forceinline__ void pv_one(f32x16& od, int vb, bf16x8 pa0, bf16x8 pa1, bf16x8 pa2, bf16x8 pa3) {
;     const s16x4 l0 = tr_read<v_rd_off(D0, 0, 0)>(vb), h0 = tr_read<v_rd_off(D0, 0, 1)>(vb), l1 = tr_read<v_rd_off(D0, 1, 0)>(vb), h1 = tr_read<v_rd_off(D0, 1, 1)>(vb);
;     const s16x4 l2 = tr_read<v_rd_off(D0, 2, 0)>(vb), h2 = tr_read<v_rd_off(D0, 2, 1)>(vb), l3 = tr_read<v_rd_off(D0, 3, 0)>(vb), h3 = tr_read<v_rd_off(D0, 3, 1)>(vb);
;     asm volatile("s_waitcnt lgkmcnt(0)" ::: "memory"); SBAR();
;     ...
;     od = __builtin_amdgcn_mfma_f32_32x32x16_bf16(pa0, PK(l0, h0), od, 0, 0, 0);
;     od = __builtin_amdgcn_mfma_f32_32x32x16_bf16(pa1, PK(l1, h1), od, 0, 0, 0);
;     od = __builtin_amdgcn_mfma_f32_32x32x16_bf16(pa2, PK(l2, h2), od, 0, 0, 0);
;     od = __builtin_amdgcn_mfma_f32_32x32x16_bf16(pa3, PK(l3, h3), od, 0, 0, 0);
;     ...
; }
; __device__ __forceinline__ void pv_d0(f32x16* o, int vb, bf16x8 pa0, bf16x8 pa1, bf16x8 pa2, bf16x8 pa3) {
;     pv_one<0>(o[0], vb, pa0, pa1, pa2, pa3); pv_one<1>(o[1], vb, pa0, pa1, pa2, pa3); pv_one<2>(o[2], vb, pa0, pa1, pa2, pa3); pv_one<3>(o[3], vb, pa0, pa1, pa2, pa3);
; __device__ __forceinline__ void finishSM(f32x16& p0, f32x16& p1, float alpha, float& l_reg, bf16x8& pa0, bf16x8& pa1, bf16x8& pa2, bf16x8& pa3) {
; #pragma unroll
;     for (int r = 0; r < 16; ++r) p1[r] = __builtin_amdgcn_exp2f(p1[r]);
;     float ps = 0;
; #pragma unroll
;     for (int r = 0; r < 16; ++r) ps += p0[r];
; #pragma unroll
;     for (int r = 0; r < 16; ++r) ps += p1[r];
;     { auto rr = __builtin_amdgcn_permlane32_swap(__float_as_uint(ps), __float_as_uint(ps), false, false);
;       ps = __uint_as_float(rr[0]) + __uint_as_float(rr[1]); }
;     l_reg = l_reg * alpha + ps;
;     ...
;     PK4(p0, 0, pa0); PK4(p0, 8, pa1); PK4(p1, 0, pa2); PK4(p1, 8, pa3);
;     ...
; }
.LBB0_187:
	v_cndmask_b32_e64 v101, v101, v142, s[14:15]
	v_mul_f32_e32 v101, 0xbe38aa3b, v101
	v_fmamk_f32 v80, v80, 0x3e38aa3b, v101
	v_fmamk_f32 v81, v81, 0x3e38aa3b, v101
	v_fmamk_f32 v102, v82, 0x3e38aa3b, v101
	v_exp_f32_e32 v82, v80
	v_fmamk_f32 v103, v84, 0x3e38aa3b, v101
	v_exp_f32_e32 v84, v81
	v_fmamk_f32 v83, v83, 0x3e38aa3b, v101
	v_exp_f32_e32 v80, v102
	v_fmamk_f32 v64, v64, 0x3e38aa3b, v101
	v_exp_f32_e32 v83, v83
	v_fmamk_f32 v104, v85, 0x3e38aa3b, v101
	v_fmamk_f32 v113, v94, 0x3e38aa3b, v101
	v_fmamk_f32 v94, v75, 0x3e38aa3b, v101
	v_exp_f32_e32 v75, v103
	v_exp_f32_e32 v102, v64
	v_add_f32_e32 v64, 0, v82
	v_fmamk_f32 v105, v86, 0x3e38aa3b, v101
	v_exp_f32_e32 v81, v104
	v_add_f32_e32 v64, v84, v64
	v_fmamk_f32 v106, v87, 0x3e38aa3b, v101
	v_fmamk_f32 v112, v93, 0x3e38aa3b, v101
	v_fmamk_f32 v93, v74, 0x3e38aa3b, v101
	v_exp_f32_e32 v74, v105
	v_add_f32_e32 v64, v80, v64
	v_fmamk_f32 v107, v88, 0x3e38aa3b, v101
	v_fmamk_f32 v114, v95, 0x3e38aa3b, v101
	v_fmamk_f32 v95, v76, 0x3e38aa3b, v101
	v_exp_f32_e32 v76, v106
	v_add_f32_e32 v64, v83, v64
	v_fmamk_f32 v108, v89, 0x3e38aa3b, v101
	v_fmamk_f32 v109, v90, 0x3e38aa3b, v101
	v_fmamk_f32 v90, v71, 0x3e38aa3b, v101
	v_exp_f32_e32 v71, v107
	v_add_f32_e32 v64, v75, v64
	v_fmamk_f32 v111, v92, 0x3e38aa3b, v101
	v_fmamk_f32 v92, v73, 0x3e38aa3b, v101
	v_exp_f32_e32 v73, v108
	v_add_f32_e32 v64, v81, v64
	v_fmamk_f32 v110, v91, 0x3e38aa3b, v101
	v_fmamk_f32 v88, v69, 0x3e38aa3b, v101
	v_exp_f32_e32 v69, v109
	v_add_f32_e32 v64, v74, v64
	v_fmamk_f32 v91, v72, 0x3e38aa3b, v101
	v_exp_f32_e32 v72, v110
	v_add_f32_e32 v64, v76, v64
	v_fmamk_f32 v86, v67, 0x3e38aa3b, v101
	v_exp_f32_e32 v67, v111
	v_add_f32_e32 v64, v71, v64
	v_fmamk_f32 v89, v70, 0x3e38aa3b, v101
	v_exp_f32_e32 v70, v112
	v_add_f32_e32 v64, v73, v64
	v_fmamk_f32 v85, v66, 0x3e38aa3b, v101
	v_exp_f32_e32 v66, v113
	v_add_f32_e32 v64, v69, v64
	v_fmamk_f32 v87, v68, 0x3e38aa3b, v101
	v_exp_f32_e32 v68, v114
	v_add_f32_e32 v64, v72, v64
	v_fmamk_f32 v65, v65, 0x3e38aa3b, v101
	v_add_f32_e32 v64, v67, v64
	v_exp_f32_e32 v103, v65
	v_add_f32_e32 v64, v70, v64
	v_exp_f32_e32 v85, v85
	v_add_f32_e32 v64, v66, v64
	v_exp_f32_e32 v86, v86
	v_add_f32_e32 v64, v68, v64
	v_exp_f32_e32 v87, v87
	v_add_f32_e32 v64, v102, v64
	v_exp_f32_e32 v88, v88
	v_add_f32_e32 v64, v103, v64
	v_exp_f32_e32 v89, v89
	v_add_f32_e32 v64, v85, v64
	v_exp_f32_e32 v90, v90
	v_add_f32_e32 v64, v86, v64
	v_exp_f32_e32 v91, v91
	v_add_f32_e32 v64, v87, v64
	v_exp_f32_e32 v92, v92
	v_add_f32_e32 v64, v88, v64
	v_exp_f32_e32 v93, v93
	v_add_f32_e32 v64, v89, v64
	v_exp_f32_e32 v94, v94
	v_add_f32_e32 v64, v90, v64
	v_fmamk_f32 v77, v77, 0x3e38aa3b, v101
	v_exp_f32_e32 v95, v95
	v_add_f32_e32 v64, v91, v64
	v_fmamk_f32 v78, v78, 0x3e38aa3b, v101
	v_exp_f32_e32 v104, v77
	v_add_f32_e32 v64, v92, v64
	v_fmac_f32_e32 v101, 0x3e38aa3b, v79
	v_exp_f32_e32 v105, v78
	v_add_f32_e32 v64, v93, v64
	v_exp_f32_e32 v101, v101
	v_add_f32_e32 v64, v94, v64
	v_add_f32_e32 v64, v95, v64
	v_add_f32_e32 v64, v104, v64
	v_add_f32_e32 v64, v105, v64
	v_add_f32_e32 v64, v101, v64
	v_mov_b32_e32 v65, v64
	s_nop 1
	v_permlane32_swap_b32_e32 v64, v65
	v_cvt_pk_bf16_f32 v78, v82, v84
	v_cvt_pk_bf16_f32 v79, v80, v83
	v_cvt_pk_bf16_f32 v80, v75, v81
	v_cvt_pk_bf16_f32 v81, v74, v76
	v_cvt_pk_bf16_f32 v74, v71, v73
	v_cvt_pk_bf16_f32 v75, v69, v72
	v_cvt_pk_bf16_f32 v76, v67, v70
	v_cvt_pk_bf16_f32 v77, v66, v68
	v_cvt_pk_bf16_f32 v66, v102, v103
	v_cvt_pk_bf16_f32 v67, v85, v86
	v_cvt_pk_bf16_f32 v68, v87, v88
	v_cvt_pk_bf16_f32 v69, v89, v90
	v_cvt_pk_bf16_f32 v70, v91, v92
	v_cvt_pk_bf16_f32 v71, v93, v94
	v_cvt_pk_bf16_f32 v72, v95, v104
	v_cvt_pk_bf16_f32 v73, v105, v101
	s_nop 0
	v_permlane32_swap_b32_e32 v78, v80
	v_permlane32_swap_b32_e32 v79, v81
	v_permlane32_swap_b32_e32 v74, v76
	v_permlane32_swap_b32_e32 v75, v77
	v_permlane32_swap_b32_e32 v66, v68
	v_permlane32_swap_b32_e32 v67, v69
	v_permlane32_swap_b32_e32 v70, v72
	v_permlane32_swap_b32_e32 v71, v73
	ds_read_b64_tr_b16 v[82:83], v179 offset:0
	ds_read_b64_tr_b16 v[84:85], v179 offset:0x800
	ds_read_b64_tr_b16 v[86:87], v179 offset:0x1000
	ds_read_b64_tr_b16 v[88:89], v179 offset:0x1800
	ds_read_b64_tr_b16 v[90:91], v179 offset:0x2000
	ds_read_b64_tr_b16 v[92:93], v179 offset:0x2800
	ds_read_b64_tr_b16 v[102:103], v179 offset:0x3000
	ds_read_b64_tr_b16 v[104:105], v179 offset:0x3800
	s_waitcnt lgkmcnt(0)
	s_nop 0
	v_mfma_f32_32x32x16_bf16 v[48:63], v[78:81], v[82:85], v[48:63]
	ds_read_b64_tr_b16 v[82:83], v179 offset:0x200
	ds_read_b64_tr_b16 v[84:85], v179 offset:0xa00
	v_mfma_f32_32x32x16_bf16 v[48:63], v[74:77], v[86:89], v[48:63]
	ds_read_b64_tr_b16 v[86:87], v179 offset:0x1200
	ds_read_b64_tr_b16 v[88:89], v179 offset:0x1a00
	v_mfma_f32_32x32x16_bf16 v[48:63], v[66:69], v[90:93], v[48:63]
	ds_read_b64_tr_b16 v[90:91], v179 offset:0x2200
	ds_read_b64_tr_b16 v[92:93], v179 offset:0x2a00
	v_mfma_f32_32x32x16_bf16 v[48:63], v[70:73], v[102:105], v[48:63]
	ds_read_b64_tr_b16 v[102:103], v179 offset:0x3200
	ds_read_b64_tr_b16 v[104:105], v179 offset:0x3a00
	s_waitcnt lgkmcnt(0)
	v_mfma_f32_32x32x16_bf16 v[32:47], v[78:81], v[82:85], v[32:47]
	ds_read_b64_tr_b16 v[82:83], v179 offset:0x400
	ds_read_b64_tr_b16 v[84:85], v179 offset:0xc00
	v_mfma_f32_32x32x16_bf16 v[32:47], v[74:77], v[86:89], v[32:47]
	ds_read_b64_tr_b16 v[86:87], v179 offset:0x1400
	ds_read_b64_tr_b16 v[88:89], v179 offset:0x1c00
	v_mfma_f32_32x32x16_bf16 v[32:47], v[66:69], v[90:93], v[32:47]
	ds_read_b64_tr_b16 v[90:91], v179 offset:0x2400
	ds_read_b64_tr_b16 v[92:93], v179 offset:0x2c00
	v_mfma_f32_32x32x16_bf16 v[32:47], v[70:73], v[102:105], v[32:47]
	ds_read_b64_tr_b16 v[102:103], v179 offset:0x3400
	ds_read_b64_tr_b16 v[104:105], v179 offset:0x3c00
	s_waitcnt lgkmcnt(0)
; __device__ __forceinline__ int crow(int r, int hi) { return (r & 3) + 8 * (r >> 2) + 4 * hi; }
; template <int DQK, int DK1, int LDQ, int LDK, int LDKR, int LDV, int NQL, int SDEPTH>
; __device__ __forceinline__ void attn_core(const AttnArgs& a, char* lds, f32x16 (&o)[4]) {
;     ...
;     pv_d0(o, vb0 + SHM_V, pa0, pa1, pa2, pa3);
;     if (hi == 0) li_l[r32] = l_reg; asm volatile("s_waitcnt lgkmcnt(0)" ::: "memory");
; #pragma unroll
;     for (int r = 0; r < 16; ++r) { const float rl = __builtin_amdgcn_rcpf(li_l[crow(r, hi)]);
; #pragma unroll
;         for (int d = 0; d < 4; ++d) o[d][r] *= rl; }
;     __syncthreads();
	v_mfma_f32_32x32x16_bf16 v[16:31], v[78:81], v[82:85], v[16:31]
	ds_read_b64_tr_b16 v[82:83], v179 offset:0x600
	ds_read_b64_tr_b16 v[84:85], v179 offset:0xe00
	v_mfma_f32_32x32x16_bf16 v[16:31], v[74:77], v[86:89], v[16:31]
	ds_read_b64_tr_b16 v[86:87], v179 offset:0x1600
	ds_read_b64_tr_b16 v[88:89], v179 offset:0x1e00
	v_mfma_f32_32x32x16_bf16 v[16:31], v[66:69], v[90:93], v[16:31]
	ds_read_b64_tr_b16 v[90:91], v179 offset:0x2600
	ds_read_b64_tr_b16 v[92:93], v179 offset:0x2e00
	v_mfma_f32_32x32x16_bf16 v[16:31], v[70:73], v[102:105], v[16:31]
	ds_read_b64_tr_b16 v[102:103], v179 offset:0x3600
	ds_read_b64_tr_b16 v[104:105], v179 offset:0x3e00
	s_waitcnt lgkmcnt(0)
	v_mfma_f32_32x32x16_bf16 v[0:15], v[78:81], v[82:85], v[0:15]
	v_mfma_f32_32x32x16_bf16 v[0:15], v[74:77], v[86:89], v[0:15]
	v_mfma_f32_32x32x16_bf16 v[0:15], v[66:69], v[90:93], v[0:15]
	v_mfma_f32_32x32x16_bf16 v[0:15], v[70:73], v[102:105], v[0:15]
	s_and_saveexec_b64 s[14:15], s[12:13]
	v_add_f32_e32 v66, v98, v99
	v_fmac_f32_e32 v66, v178, v143
	v_add_f32_e32 v64, v64, v65
	v_fmac_f32_e32 v64, v66, v100
	ds_write_b32 v177, v64 offset:49152
	s_or_b64 exec, exec, s[14:15]
	s_waitcnt lgkmcnt(0)
	v_add_u32_e32 v82, v161, v96
	ds_read_b128 v[74:77], v82 offset:49152
	ds_read_b128 v[78:81], v82 offset:49184
	v_mov_b32_e32 v68, v16
	s_nop 0
	v_mov_b32_e32 v69, v0
	v_mov_b32_e32 v0, v17
	s_waitcnt lgkmcnt(1)
	v_rcp_f32_e32 v16, v75
	v_rcp_f32_e32 v66, v74
	v_mov_b32_e32 v64, v48
	v_mov_b32_e32 v65, v32
	v_pk_mul_f32 v[70:71], v[0:1], v[16:17] op_sel_hi:[1,0]
	v_rcp_f32_e32 v0, v76
	v_mov_b32_e32 v32, v49
	v_pk_mul_f32 v[64:65], v[64:65], v[66:67] op_sel_hi:[1,0]
	v_pk_mul_f32 v[66:67], v[68:69], v[66:67] op_sel_hi:[1,0]
	v_pk_mul_f32 v[68:69], v[32:33], v[16:17] op_sel_hi:[1,0]
	v_mov_b32_e32 v16, v50
	v_mov_b32_e32 v17, v34
	v_pk_mul_f32 v[72:73], v[16:17], v[0:1] op_sel_hi:[1,0]
	v_mov_b32_e32 v16, v18
	v_mov_b32_e32 v17, v2
	v_pk_mul_f32 v[74:75], v[16:17], v[0:1] op_sel_hi:[1,0]
	v_rcp_f32_e32 v16, v77
	v_mov_b32_e32 v32, v20
	s_waitcnt lgkmcnt(0)
	v_rcp_f32_e32 v20, v79
	v_mov_b32_e32 v34, v51
	v_rcp_f32_e32 v18, v78
	v_mov_b32_e32 v33, v4
	v_mov_b32_e32 v4, v21
	v_pk_mul_f32 v[0:1], v[34:35], v[16:17] op_sel_hi:[1,0]
	v_pk_mul_f32 v[34:35], v[4:5], v[20:21] op_sel_hi:[1,0]
	v_rcp_f32_e32 v4, v80
	ds_read_b128 v[76:79], v82 offset:49216
	v_mov_b32_e32 v2, v19
	v_pk_mul_f32 v[2:3], v[2:3], v[16:17] op_sel_hi:[1,0]
	v_mov_b32_e32 v16, v52
	v_mov_b32_e32 v17, v36
	v_mov_b32_e32 v36, v53
	v_pk_mul_f32 v[16:17], v[16:17], v[18:19] op_sel_hi:[1,0]
	v_pk_mul_f32 v[18:19], v[32:33], v[18:19] op_sel_hi:[1,0]
	v_pk_mul_f32 v[32:33], v[36:37], v[20:21] op_sel_hi:[1,0]
	v_mov_b32_e32 v20, v54
	v_mov_b32_e32 v21, v38
	v_pk_mul_f32 v[48:49], v[20:21], v[4:5] op_sel_hi:[1,0]
	v_mov_b32_e32 v20, v22
	v_mov_b32_e32 v21, v6
	v_pk_mul_f32 v[50:51], v[20:21], v[4:5] op_sel_hi:[1,0]
	v_rcp_f32_e32 v20, v81
	v_mov_b32_e32 v36, v24
	s_waitcnt lgkmcnt(0)
	v_rcp_f32_e32 v24, v77
	v_mov_b32_e32 v38, v55
	v_rcp_f32_e32 v22, v76
	v_mov_b32_e32 v37, v8
	v_mov_b32_e32 v8, v25
	v_pk_mul_f32 v[4:5], v[38:39], v[20:21] op_sel_hi:[1,0]
	v_pk_mul_f32 v[38:39], v[8:9], v[24:25] op_sel_hi:[1,0]
	v_rcp_f32_e32 v8, v78
	v_mov_b32_e32 v6, v23
	v_pk_mul_f32 v[6:7], v[6:7], v[20:21] op_sel_hi:[1,0]
	v_mov_b32_e32 v20, v56
	v_mov_b32_e32 v21, v40
	v_mov_b32_e32 v40, v57
	v_pk_mul_f32 v[20:21], v[20:21], v[22:23] op_sel_hi:[1,0]
	v_pk_mul_f32 v[22:23], v[36:37], v[22:23] op_sel_hi:[1,0]
	v_pk_mul_f32 v[36:37], v[40:41], v[24:25] op_sel_hi:[1,0]
	v_mov_b32_e32 v24, v58
	v_mov_b32_e32 v25, v42
	v_pk_mul_f32 v[52:53], v[24:25], v[8:9] op_sel_hi:[1,0]
	v_mov_b32_e32 v24, v26
	v_mov_b32_e32 v25, v10
	v_pk_mul_f32 v[54:55], v[24:25], v[8:9] op_sel_hi:[1,0]
	v_rcp_f32_e32 v24, v79
	ds_read_b128 v[76:79], v82 offset:49248
	v_mov_b32_e32 v40, v28
	v_mov_b32_e32 v42, v59
	v_mov_b32_e32 v41, v12
	v_mov_b32_e32 v12, v29
	s_waitcnt lgkmcnt(0)
	v_rcp_f32_e32 v28, v77
	v_rcp_f32_e32 v26, v76
	v_pk_mul_f32 v[8:9], v[42:43], v[24:25] op_sel_hi:[1,0]
	v_mov_b32_e32 v10, v27
	v_pk_mul_f32 v[42:43], v[12:13], v[28:29] op_sel_hi:[1,0]
	v_rcp_f32_e32 v12, v78
	v_pk_mul_f32 v[10:11], v[10:11], v[24:25] op_sel_hi:[1,0]
	v_mov_b32_e32 v24, v60
	v_mov_b32_e32 v25, v44
	v_mov_b32_e32 v44, v61
	v_pk_mul_f32 v[24:25], v[24:25], v[26:27] op_sel_hi:[1,0]
	v_pk_mul_f32 v[26:27], v[40:41], v[26:27] op_sel_hi:[1,0]
	v_pk_mul_f32 v[40:41], v[44:45], v[28:29] op_sel_hi:[1,0]
	v_mov_b32_e32 v28, v62
	v_mov_b32_e32 v29, v46
	v_pk_mul_f32 v[56:57], v[28:29], v[12:13] op_sel_hi:[1,0]
	v_mov_b32_e32 v28, v30
	v_mov_b32_e32 v29, v14
	v_pk_mul_f32 v[58:59], v[28:29], v[12:13] op_sel_hi:[1,0]
	v_rcp_f32_e32 v28, v79
	v_mov_b32_e32 v46, v63
	v_mov_b32_e32 v14, v31
	s_mov_b64 s[12:13], -1
	v_pk_mul_f32 v[12:13], v[46:47], v[28:29] op_sel_hi:[1,0]
	v_pk_mul_f32 v[14:15], v[14:15], v[28:29] op_sel_hi:[1,0]
	v_mov_b64_e32 v[28:29], v[154:155]
	s_and_b64 vcc, exec, s[94:95]
	s_barrier
	s_cbranch_vccz .LBB0_191
; __device__ __forceinline__ void phase_attn_diff(const Params& p, char* lds) {
;     ...
;             } else {
;                 bf16_t* Ow = O + (size_t)(row0 + wid * 32 + 4 * hi) * 1024 + h * 128 + r32;
;                 asm volatile("" : "+v"(Ow));
; #pragma unroll
;                 for (int r = 0; r < 16; ++r) {
;                     const f32x4 t = *(const f32x4*)(scr + 4 * r);
;                     const float v0 = t[0] - lam * o[0][r], v1 = t[1] - lam * o[1][r], v2 = t[2] - lam * o[2][r], v3 = t[3] - lam * o[3][r];
;                     float ss = v0 * v0 + v1 * v1 + v2 * v2 + v3 * v3;
	global_load_dwordx4 v[84:87], v[28:29], off
	global_load_dwordx4 v[88:91], v[28:29], off offset:16
	global_load_dwordx4 v[92:95], v[28:29], off offset:32
	global_load_dwordx4 v[100:103], v[28:29], off offset:48
	global_load_dwordx4 v[104:107], v[28:29], off offset:64
	global_load_dwordx4 v[108:111], v[28:29], off offset:80
	global_load_dwordx4 v[112:115], v[28:29], off offset:96
	global_load_dwordx4 v[116:119], v[28:29], off offset:112
	global_load_dwordx4 v[120:123], v[28:29], off offset:128
	global_load_dwordx4 v[124:127], v[28:29], off offset:144
	global_load_dwordx4 v[128:131], v[28:29], off offset:160
	global_load_dwordx4 v[132:135], v[28:29], off offset:176
	global_load_dwordx4 v[136:139], v[28:29], off offset:192
	global_load_dwordx4 v[140:143], v[28:29], off offset:208
	global_load_dwordx4 v[144:147], v[28:29], off offset:224
	global_load_dwordx4 v[148:151], v[28:29], off offset:240
	v_mov_b64_e32 v[30:31], v[162:163]
	v_xor_b32_e32 v44, 16, v183
	v_xor_b32_e32 v45, 8, v183
	v_xor_b32_e32 v46, 4, v183
	v_xor_b32_e32 v47, 2, v183
	v_xor_b32_e32 v60, 1, v183
	v_lshlrev_b32_e32 v44, 2, v44
	v_lshlrev_b32_e32 v45, 2, v45
	v_lshlrev_b32_e32 v46, 2, v46
	v_lshlrev_b32_e32 v47, 2, v47
	v_lshlrev_b32_e32 v60, 2, v60
	s_mov_b32 s2, 0xd000
	s_waitcnt vmcnt(0) lgkmcnt(0)
	v_pk_fma_f32 v[84:85], v[156:157], v[64:65], v[84:85] neg_lo:[1,0,0] neg_hi:[1,0,0]
	v_pk_fma_f32 v[86:87], v[156:157], v[66:67], v[86:87] neg_lo:[1,0,0] neg_hi:[1,0,0]
	v_pk_fma_f32 v[88:89], v[156:157], v[68:69], v[88:89] neg_lo:[1,0,0] neg_hi:[1,0,0]
	v_pk_fma_f32 v[90:91], v[156:157], v[70:71], v[90:91] neg_lo:[1,0,0] neg_hi:[1,0,0]
	v_pk_fma_f32 v[92:93], v[156:157], v[72:73], v[92:93] neg_lo:[1,0,0] neg_hi:[1,0,0]
	v_pk_fma_f32 v[94:95], v[156:157], v[74:75], v[94:95] neg_lo:[1,0,0] neg_hi:[1,0,0]
	v_pk_fma_f32 v[100:101], v[156:157], v[0:1], v[100:101] neg_lo:[1,0,0] neg_hi:[1,0,0]
	v_pk_fma_f32 v[102:103], v[156:157], v[2:3], v[102:103] neg_lo:[1,0,0] neg_hi:[1,0,0]
	v_pk_fma_f32 v[104:105], v[156:157], v[16:17], v[104:105] neg_lo:[1,0,0] neg_hi:[1,0,0]
	v_pk_fma_f32 v[106:107], v[156:157], v[18:19], v[106:107] neg_lo:[1,0,0] neg_hi:[1,0,0]
	v_pk_fma_f32 v[108:109], v[156:157], v[32:33], v[108:109] neg_lo:[1,0,0] neg_hi:[1,0,0]
	v_pk_fma_f32 v[110:111], v[156:157], v[34:35], v[110:111] neg_lo:[1,0,0] neg_hi:[1,0,0]
	v_pk_fma_f32 v[112:113], v[156:157], v[48:49], v[112:113] neg_lo:[1,0,0] neg_hi:[1,0,0]
	v_pk_fma_f32 v[114:115], v[156:157], v[50:51], v[114:115] neg_lo:[1,0,0] neg_hi:[1,0,0]
	v_pk_fma_f32 v[116:117], v[156:157], v[4:5], v[116:117] neg_lo:[1,0,0] neg_hi:[1,0,0]
	v_pk_fma_f32 v[118:119], v[156:157], v[6:7], v[118:119] neg_lo:[1,0,0] neg_hi:[1,0,0]
	v_pk_fma_f32 v[120:121], v[156:157], v[20:21], v[120:121] neg_lo:[1,0,0] neg_hi:[1,0,0]
	v_pk_fma_f32 v[122:123], v[156:157], v[22:23], v[122:123] neg_lo:[1,0,0] neg_hi:[1,0,0]
	v_pk_fma_f32 v[124:125], v[156:157], v[36:37], v[124:125] neg_lo:[1,0,0] neg_hi:[1,0,0]
	v_pk_fma_f32 v[126:127], v[156:157], v[38:39], v[126:127] neg_lo:[1,0,0] neg_hi:[1,0,0]
	v_pk_fma_f32 v[128:129], v[156:157], v[52:53], v[128:129] neg_lo:[1,0,0] neg_hi:[1,0,0]
	v_pk_fma_f32 v[130:131], v[156:157], v[54:55], v[130:131] neg_lo:[1,0,0] neg_hi:[1,0,0]
	v_pk_fma_f32 v[132:133], v[156:157], v[8:9], v[132:133] neg_lo:[1,0,0] neg_hi:[1,0,0]
	v_pk_fma_f32 v[134:135], v[156:157], v[10:11], v[134:135] neg_lo:[1,0,0] neg_hi:[1,0,0]
	v_pk_fma_f32 v[136:137], v[156:157], v[24:25], v[136:137] neg_lo:[1,0,0] neg_hi:[1,0,0]
	v_pk_fma_f32 v[138:139], v[156:157], v[26:27], v[138:139] neg_lo:[1,0,0] neg_hi:[1,0,0]
	v_pk_fma_f32 v[140:141], v[156:157], v[40:41], v[140:141] neg_lo:[1,0,0] neg_hi:[1,0,0]
	v_pk_fma_f32 v[142:143], v[156:157], v[42:43], v[142:143] neg_lo:[1,0,0] neg_hi:[1,0,0]
	v_pk_fma_f32 v[144:145], v[156:157], v[56:57], v[144:145] neg_lo:[1,0,0] neg_hi:[1,0,0]
	v_pk_fma_f32 v[146:147], v[156:157], v[58:59], v[146:147] neg_lo:[1,0,0] neg_hi:[1,0,0]
	v_pk_fma_f32 v[148:149], v[156:157], v[12:13], v[148:149] neg_lo:[1,0,0] neg_hi:[1,0,0]
	v_pk_fma_f32 v[150:151], v[156:157], v[14:15], v[150:151] neg_lo:[1,0,0] neg_hi:[1,0,0]
	v_pk_mul_f32 v[64:65], v[84:85], v[84:85]
	v_pk_mul_f32 v[66:67], v[86:87], v[86:87]
	v_pk_mul_f32 v[68:69], v[88:89], v[88:89]
	v_pk_mul_f32 v[70:71], v[90:91], v[90:91]
	v_pk_mul_f32 v[72:73], v[92:93], v[92:93]
	v_pk_mul_f32 v[74:75], v[94:95], v[94:95]
	v_pk_mul_f32 v[0:1], v[100:101], v[100:101]
	v_pk_mul_f32 v[2:3], v[102:103], v[102:103]
	v_pk_mul_f32 v[16:17], v[104:105], v[104:105]
	v_pk_mul_f32 v[18:19], v[106:107], v[106:107]
	v_pk_mul_f32 v[32:33], v[108:109], v[108:109]
	v_pk_mul_f32 v[34:35], v[110:111], v[110:111]
	v_pk_mul_f32 v[48:49], v[112:113], v[112:113]
	v_pk_mul_f32 v[50:51], v[114:115], v[114:115]
	v_pk_mul_f32 v[4:5], v[116:117], v[116:117]
	v_pk_mul_f32 v[6:7], v[118:119], v[118:119]
	v_pk_mul_f32 v[20:21], v[120:121], v[120:121]
	v_pk_mul_f32 v[22:23], v[122:123], v[122:123]
	v_pk_mul_f32 v[36:37], v[124:125], v[124:125]
	v_pk_mul_f32 v[38:39], v[126:127], v[126:127]
	v_pk_mul_f32 v[52:53], v[128:129], v[128:129]
	v_pk_mul_f32 v[54:55], v[130:131], v[130:131]
	v_pk_mul_f32 v[8:9], v[132:133], v[132:133]
	v_pk_mul_f32 v[10:11], v[134:135], v[134:135]
	v_pk_mul_f32 v[24:25], v[136:137], v[136:137]
	v_pk_mul_f32 v[26:27], v[138:139], v[138:139]
	v_pk_mul_f32 v[40:41], v[140:141], v[140:141]
	v_pk_mul_f32 v[42:43], v[142:143], v[142:143]
	v_pk_mul_f32 v[56:57], v[144:145], v[144:145]
	v_pk_mul_f32 v[58:59], v[146:147], v[146:147]
	v_pk_mul_f32 v[12:13], v[148:149], v[148:149]
	v_pk_mul_f32 v[14:15], v[150:151], v[150:151]
	v_add_f32_e32 v64, v64, v65
	v_add_f32_e32 v68, v68, v69
; __device__ __forceinline__ void phase_attn_diff(const Params& p, char* lds) {
;     ...
;                 for (int r = 0; r < 16; ++r) {
;                     const f32x4 t = *(const f32x4*)(scr + 4 * r);
;                     const float v0 = t[0] - lam * o[0][r], v1 = t[1] - lam * o[1][r], v2 = t[2] - lam * o[2][r], v3 = t[3] - lam * o[3][r];
;                     float ss = v0 * v0 + v1 * v1 + v2 * v2 + v3 * v3;
; #pragma unroll
;                     for (int x = 16; x >= 1; x >>= 1) ss += __shfl_xor(ss, x);
;                     const float rs = rsqrtf(ss * (1.0f / 128.0f) + EPS);
	v_add_f32_e32 v72, v72, v73
	v_add_f32_e32 v0, v0, v1
	v_add_f32_e32 v16, v16, v17
	v_add_f32_e32 v32, v32, v33
	v_add_f32_e32 v48, v48, v49
	v_add_f32_e32 v4, v4, v5
	v_add_f32_e32 v20, v20, v21
	v_add_f32_e32 v36, v36, v37
	v_add_f32_e32 v52, v52, v53
	v_add_f32_e32 v8, v8, v9
	v_add_f32_e32 v24, v24, v25
	v_add_f32_e32 v40, v40, v41
	v_add_f32_e32 v56, v56, v57
	v_add_f32_e32 v12, v12, v13
	v_add_f32_e32 v64, v66, v64
	v_add_f32_e32 v68, v70, v68
	v_add_f32_e32 v72, v74, v72
	v_add_f32_e32 v0, v2, v0
	v_add_f32_e32 v16, v18, v16
	v_add_f32_e32 v32, v34, v32
	v_add_f32_e32 v48, v50, v48
	v_add_f32_e32 v4, v6, v4
	v_add_f32_e32 v20, v22, v20
	v_add_f32_e32 v36, v38, v36
	v_add_f32_e32 v52, v54, v52
	v_add_f32_e32 v8, v10, v8
	v_add_f32_e32 v24, v26, v24
	v_add_f32_e32 v40, v42, v40
	v_add_f32_e32 v56, v58, v56
	v_add_f32_e32 v12, v14, v12
	v_add_f32_e32 v64, v67, v64
	v_add_f32_e32 v68, v71, v68
	v_add_f32_e32 v72, v75, v72
	v_add_f32_e32 v0, v3, v0
	v_add_f32_e32 v16, v19, v16
	v_add_f32_e32 v32, v35, v32
	v_add_f32_e32 v48, v51, v48
	v_add_f32_e32 v4, v7, v4
	v_add_f32_e32 v20, v23, v20
	v_add_f32_e32 v36, v39, v36
	v_add_f32_e32 v52, v55, v52
	v_add_f32_e32 v8, v11, v8
	v_add_f32_e32 v24, v27, v24
	v_add_f32_e32 v40, v43, v40
	v_add_f32_e32 v56, v59, v56
	v_add_f32_e32 v12, v15, v12
	v_mov_b32_e32 v65, v64
	v_mov_b32_e32 v69, v68
	v_mov_b32_e32 v73, v72
	v_mov_b32_e32 v1, v0
	v_mov_b32_e32 v17, v16
	v_mov_b32_e32 v33, v32
	v_mov_b32_e32 v49, v48
	v_mov_b32_e32 v5, v4
	v_mov_b32_e32 v21, v20
	v_mov_b32_e32 v37, v36
	v_mov_b32_e32 v53, v52
	v_mov_b32_e32 v9, v8
	v_mov_b32_e32 v25, v24
	v_mov_b32_e32 v41, v40
	v_mov_b32_e32 v57, v56
	v_mov_b32_e32 v13, v12
	v_permlane16_swap_b32_e32 v64, v65
	v_permlane16_swap_b32_e32 v68, v69
	v_permlane16_swap_b32_e32 v72, v73
	v_permlane16_swap_b32_e32 v0, v1
	v_permlane16_swap_b32_e32 v16, v17
	v_permlane16_swap_b32_e32 v32, v33
	v_permlane16_swap_b32_e32 v48, v49
	v_permlane16_swap_b32_e32 v4, v5
	v_permlane16_swap_b32_e32 v20, v21
	v_permlane16_swap_b32_e32 v36, v37
	v_permlane16_swap_b32_e32 v52, v53
	v_permlane16_swap_b32_e32 v8, v9
	v_permlane16_swap_b32_e32 v24, v25
	v_permlane16_swap_b32_e32 v40, v41
	v_permlane16_swap_b32_e32 v56, v57
	v_permlane16_swap_b32_e32 v12, v13
	v_add_f32_e32 v64, v64, v65
	v_add_f32_e32 v68, v68, v69
	v_add_f32_e32 v72, v72, v73
	v_add_f32_e32 v0, v0, v1
	v_add_f32_e32 v16, v16, v17
	v_add_f32_e32 v32, v32, v33
	v_add_f32_e32 v48, v48, v49
	v_add_f32_e32 v4, v4, v5
	v_add_f32_e32 v20, v20, v21
	v_add_f32_e32 v36, v36, v37
	v_add_f32_e32 v52, v52, v53
	v_add_f32_e32 v8, v8, v9
	v_add_f32_e32 v24, v24, v25
	v_add_f32_e32 v40, v40, v41
	v_add_f32_e32 v56, v56, v57
	v_add_f32_e32 v12, v12, v13
	v_add_f32_dpp v64, v64, v64 row_ror:8 row_mask:0xf bank_mask:0xf
	v_add_f32_dpp v68, v68, v68 row_ror:8 row_mask:0xf bank_mask:0xf
	v_add_f32_dpp v72, v72, v72 row_ror:8 row_mask:0xf bank_mask:0xf
	v_add_f32_dpp v0, v0, v0 row_ror:8 row_mask:0xf bank_mask:0xf
	v_add_f32_dpp v16, v16, v16 row_ror:8 row_mask:0xf bank_mask:0xf
	v_add_f32_dpp v32, v32, v32 row_ror:8 row_mask:0xf bank_mask:0xf
	v_add_f32_dpp v48, v48, v48 row_ror:8 row_mask:0xf bank_mask:0xf
	v_add_f32_dpp v4, v4, v4 row_ror:8 row_mask:0xf bank_mask:0xf
	v_add_f32_dpp v20, v20, v20 row_ror:8 row_mask:0xf bank_mask:0xf
	v_add_f32_dpp v36, v36, v36 row_ror:8 row_mask:0xf bank_mask:0xf
	v_add_f32_dpp v52, v52, v52 row_ror:8 row_mask:0xf bank_mask:0xf
	v_add_f32_dpp v8, v8, v8 row_ror:8 row_mask:0xf bank_mask:0xf
	v_add_f32_dpp v24, v24, v24 row_ror:8 row_mask:0xf bank_mask:0xf
	v_add_f32_dpp v40, v40, v40 row_ror:8 row_mask:0xf bank_mask:0xf
	v_add_f32_dpp v56, v56, v56 row_ror:8 row_mask:0xf bank_mask:0xf
	v_add_f32_dpp v12, v12, v12 row_ror:8 row_mask:0xf bank_mask:0xf
	v_add_f32_dpp v64, v64, v64 row_ror:4 row_mask:0xf bank_mask:0xf
	v_add_f32_dpp v68, v68, v68 row_ror:4 row_mask:0xf bank_mask:0xf
	v_add_f32_dpp v72, v72, v72 row_ror:4 row_mask:0xf bank_mask:0xf
	v_add_f32_dpp v0, v0, v0 row_ror:4 row_mask:0xf bank_mask:0xf
	v_add_f32_dpp v16, v16, v16 row_ror:4 row_mask:0xf bank_mask:0xf
	v_add_f32_dpp v32, v32, v32 row_ror:4 row_mask:0xf bank_mask:0xf
	v_add_f32_dpp v48, v48, v48 row_ror:4 row_mask:0xf bank_mask:0xf
	v_add_f32_dpp v4, v4, v4 row_ror:4 row_mask:0xf bank_mask:0xf
	v_add_f32_dpp v20, v20, v20 row_ror:4 row_mask:0xf bank_mask:0xf
	v_add_f32_dpp v36, v36, v36 row_ror:4 row_mask:0xf bank_mask:0xf
	v_add_f32_dpp v52, v52, v52 row_ror:4 row_mask:0xf bank_mask:0xf
	v_add_f32_dpp v8, v8, v8 row_ror:4 row_mask:0xf bank_mask:0xf
	v_add_f32_dpp v24, v24, v24 row_ror:4 row_mask:0xf bank_mask:0xf
	v_add_f32_dpp v40, v40, v40 row_ror:4 row_mask:0xf bank_mask:0xf
	v_add_f32_dpp v56, v56, v56 row_ror:4 row_mask:0xf bank_mask:0xf
	v_add_f32_dpp v12, v12, v12 row_ror:4 row_mask:0xf bank_mask:0xf
	v_add_f32_dpp v64, v64, v64 row_ror:2 row_mask:0xf bank_mask:0xf
	v_add_f32_dpp v68, v68, v68 row_ror:2 row_mask:0xf bank_mask:0xf
	v_add_f32_dpp v72, v72, v72 row_ror:2 row_mask:0xf bank_mask:0xf
	v_add_f32_dpp v0, v0, v0 row_ror:2 row_mask:0xf bank_mask:0xf
	v_add_f32_dpp v16, v16, v16 row_ror:2 row_mask:0xf bank_mask:0xf
	v_add_f32_dpp v32, v32, v32 row_ror:2 row_mask:0xf bank_mask:0xf
	v_add_f32_dpp v48, v48, v48 row_ror:2 row_mask:0xf bank_mask:0xf
	v_add_f32_dpp v4, v4, v4 row_ror:2 row_mask:0xf bank_mask:0xf
	v_add_f32_dpp v20, v20, v20 row_ror:2 row_mask:0xf bank_mask:0xf
	v_add_f32_dpp v36, v36, v36 row_ror:2 row_mask:0xf bank_mask:0xf
	v_add_f32_dpp v52, v52, v52 row_ror:2 row_mask:0xf bank_mask:0xf
	v_add_f32_dpp v8, v8, v8 row_ror:2 row_mask:0xf bank_mask:0xf
	v_add_f32_dpp v24, v24, v24 row_ror:2 row_mask:0xf bank_mask:0xf
; __device__ __forceinline__ void phase_attn_diff(const Params& p, char* lds) {
;     ...
; #pragma unroll
;                     for (int x = 16; x >= 1; x >>= 1) ss += __shfl_xor(ss, x);
;                     const float rs = rsqrtf(ss * (1.0f / 128.0f) + EPS);
	v_add_f32_dpp v40, v40, v40 row_ror:2 row_mask:0xf bank_mask:0xf
	v_add_f32_dpp v56, v56, v56 row_ror:2 row_mask:0xf bank_mask:0xf
	v_add_f32_dpp v12, v12, v12 row_ror:2 row_mask:0xf bank_mask:0xf
	v_add_f32_dpp v64, v64, v64 row_ror:1 row_mask:0xf bank_mask:0xf
	v_add_f32_dpp v68, v68, v68 row_ror:1 row_mask:0xf bank_mask:0xf
	v_add_f32_dpp v72, v72, v72 row_ror:1 row_mask:0xf bank_mask:0xf
	v_add_f32_dpp v0, v0, v0 row_ror:1 row_mask:0xf bank_mask:0xf
	v_add_f32_dpp v16, v16, v16 row_ror:1 row_mask:0xf bank_mask:0xf
	v_add_f32_dpp v32, v32, v32 row_ror:1 row_mask:0xf bank_mask:0xf
	v_add_f32_dpp v48, v48, v48 row_ror:1 row_mask:0xf bank_mask:0xf
	v_add_f32_dpp v4, v4, v4 row_ror:1 row_mask:0xf bank_mask:0xf
	v_add_f32_dpp v20, v20, v20 row_ror:1 row_mask:0xf bank_mask:0xf
	v_add_f32_dpp v36, v36, v36 row_ror:1 row_mask:0xf bank_mask:0xf
	v_add_f32_dpp v52, v52, v52 row_ror:1 row_mask:0xf bank_mask:0xf
	v_add_f32_dpp v8, v8, v8 row_ror:1 row_mask:0xf bank_mask:0xf
	v_add_f32_dpp v24, v24, v24 row_ror:1 row_mask:0xf bank_mask:0xf
	v_add_f32_dpp v40, v40, v40 row_ror:1 row_mask:0xf bank_mask:0xf
	v_add_f32_dpp v56, v56, v56 row_ror:1 row_mask:0xf bank_mask:0xf
	v_add_f32_dpp v12, v12, v12 row_ror:1 row_mask:0xf bank_mask:0xf
	v_fmamk_f32 v64, v64, 0x3c000000, v158
	v_cmp_gt_f32_e32 vcc, s82, v64
	v_mul_f32_e32 v65, 0x4b800000, v64
	s_nop 0
	v_cndmask_b32_e32 v64, v64, v65, vcc
	v_rsq_f32_e32 v64, v64
	s_nop 0
	v_mul_f32_e32 v65, 0x45800000, v64
	v_cndmask_b32_e32 v64, v64, v65, vcc
	v_fmamk_f32 v68, v68, 0x3c000000, v158
	v_cmp_gt_f32_e32 vcc, s82, v68
	v_mul_f32_e32 v69, 0x4b800000, v68
	s_nop 0
	v_cndmask_b32_e32 v68, v68, v69, vcc
	v_rsq_f32_e32 v68, v68
	s_nop 0
	v_mul_f32_e32 v69, 0x45800000, v68
	v_cndmask_b32_e32 v68, v68, v69, vcc
	v_fmamk_f32 v72, v72, 0x3c000000, v158
	v_cmp_gt_f32_e32 vcc, s82, v72
	v_mul_f32_e32 v73, 0x4b800000, v72
	s_nop 0
	v_cndmask_b32_e32 v72, v72, v73, vcc
	v_rsq_f32_e32 v72, v72
	s_nop 0
	v_mul_f32_e32 v73, 0x45800000, v72
	v_cndmask_b32_e32 v72, v72, v73, vcc
	v_fmamk_f32 v0, v0, 0x3c000000, v158
	v_cmp_gt_f32_e32 vcc, s82, v0
	v_mul_f32_e32 v1, 0x4b800000, v0
	s_nop 0
	v_cndmask_b32_e32 v0, v0, v1, vcc
	v_rsq_f32_e32 v0, v0
	s_nop 0
	v_mul_f32_e32 v1, 0x45800000, v0
	v_cndmask_b32_e32 v0, v0, v1, vcc
	v_fmamk_f32 v16, v16, 0x3c000000, v158
	v_cmp_gt_f32_e32 vcc, s82, v16
	v_mul_f32_e32 v17, 0x4b800000, v16
	s_nop 0
	v_cndmask_b32_e32 v16, v16, v17, vcc
	v_rsq_f32_e32 v16, v16
	s_nop 0
	v_mul_f32_e32 v17, 0x45800000, v16
	v_cndmask_b32_e32 v16, v16, v17, vcc
	v_fmamk_f32 v32, v32, 0x3c000000, v158
	v_cmp_gt_f32_e32 vcc, s82, v32
	v_mul_f32_e32 v33, 0x4b800000, v32
	s_nop 0
	v_cndmask_b32_e32 v32, v32, v33, vcc
	v_rsq_f32_e32 v32, v32
	s_nop 0
	v_mul_f32_e32 v33, 0x45800000, v32
	v_cndmask_b32_e32 v32, v32, v33, vcc
	v_fmamk_f32 v48, v48, 0x3c000000, v158
	v_cmp_gt_f32_e32 vcc, s82, v48
	v_mul_f32_e32 v49, 0x4b800000, v48
	s_nop 0
	v_cndmask_b32_e32 v48, v48, v49, vcc
	v_rsq_f32_e32 v48, v48
	s_nop 0
	v_mul_f32_e32 v49, 0x45800000, v48
	v_cndmask_b32_e32 v48, v48, v49, vcc
	v_fmamk_f32 v4, v4, 0x3c000000, v158
	v_cmp_gt_f32_e32 vcc, s82, v4
	v_mul_f32_e32 v5, 0x4b800000, v4
	s_nop 0
	v_cndmask_b32_e32 v4, v4, v5, vcc
	v_rsq_f32_e32 v4, v4
	s_nop 0
	v_mul_f32_e32 v5, 0x45800000, v4
	v_cndmask_b32_e32 v4, v4, v5, vcc
	v_fmamk_f32 v20, v20, 0x3c000000, v158
	v_cmp_gt_f32_e32 vcc, s82, v20
	v_mul_f32_e32 v21, 0x4b800000, v20
	s_nop 0
	v_cndmask_b32_e32 v20, v20, v21, vcc
	v_rsq_f32_e32 v20, v20
	s_nop 0
	v_mul_f32_e32 v21, 0x45800000, v20
	v_cndmask_b32_e32 v20, v20, v21, vcc
	v_fmamk_f32 v36, v36, 0x3c000000, v158
	v_cmp_gt_f32_e32 vcc, s82, v36
	v_mul_f32_e32 v37, 0x4b800000, v36
	s_nop 0
	v_cndmask_b32_e32 v36, v36, v37, vcc
	v_rsq_f32_e32 v36, v36
	s_nop 0
	v_mul_f32_e32 v37, 0x45800000, v36
	v_cndmask_b32_e32 v36, v36, v37, vcc
	v_fmamk_f32 v52, v52, 0x3c000000, v158
	v_cmp_gt_f32_e32 vcc, s82, v52
	v_mul_f32_e32 v53, 0x4b800000, v52
	s_nop 0
	v_cndmask_b32_e32 v52, v52, v53, vcc
	v_rsq_f32_e32 v52, v52
	s_nop 0
	v_mul_f32_e32 v53, 0x45800000, v52
	v_cndmask_b32_e32 v52, v52, v53, vcc
	v_fmamk_f32 v8, v8, 0x3c000000, v158
	v_cmp_gt_f32_e32 vcc, s82, v8
	v_mul_f32_e32 v9, 0x4b800000, v8
	s_nop 0
	v_cndmask_b32_e32 v8, v8, v9, vcc
	v_rsq_f32_e32 v8, v8
	s_nop 0
	v_mul_f32_e32 v9, 0x45800000, v8
	v_cndmask_b32_e32 v8, v8, v9, vcc
	v_fmamk_f32 v24, v24, 0x3c000000, v158
	v_cmp_gt_f32_e32 vcc, s82, v24
	v_mul_f32_e32 v25, 0x4b800000, v24
	s_nop 0
	v_cndmask_b32_e32 v24, v24, v25, vcc
	v_rsq_f32_e32 v24, v24
	s_nop 0
	v_mul_f32_e32 v25, 0x45800000, v24
	v_cndmask_b32_e32 v24, v24, v25, vcc
	v_fmamk_f32 v40, v40, 0x3c000000, v158
	v_cmp_gt_f32_e32 vcc, s82, v40
	v_mul_f32_e32 v41, 0x4b800000, v40
	s_nop 0
	v_cndmask_b32_e32 v40, v40, v41, vcc
	v_rsq_f32_e32 v40, v40
	s_nop 0
	v_mul_f32_e32 v41, 0x45800000, v40
	v_cndmask_b32_e32 v40, v40, v41, vcc
	v_fmamk_f32 v56, v56, 0x3c000000, v158
	v_cmp_gt_f32_e32 vcc, s82, v56
	v_mul_f32_e32 v57, 0x4b800000, v56
	s_nop 0
	v_cndmask_b32_e32 v56, v56, v57, vcc
	v_rsq_f32_e32 v56, v56
	s_nop 0
	v_mul_f32_e32 v57, 0x45800000, v56
	v_cndmask_b32_e32 v56, v56, v57, vcc
	v_fmamk_f32 v12, v12, 0x3c000000, v158
	v_cmp_gt_f32_e32 vcc, s82, v12
	v_mul_f32_e32 v13, 0x4b800000, v12
	s_nop 0
	v_cndmask_b32_e32 v12, v12, v13, vcc
	v_rsq_f32_e32 v12, v12
	s_nop 0
	v_mul_f32_e32 v13, 0x45800000, v12
	v_cndmask_b32_e32 v12, v12, v13, vcc
	v_add_co_u32_e32 v66, vcc, s83, v30
	s_nop 1
	v_addc_co_u32_e32 v67, vcc, 0, v31, vcc
	v_add_co_u32_e32 v70, vcc, s54, v30
	s_nop 1
	v_addc_co_u32_e32 v71, vcc, 0, v31, vcc
	v_add_co_u32_e32 v74, vcc, s59, v30
	s_nop 1
	v_addc_co_u32_e32 v75, vcc, 0, v31, vcc
; __device__ __forceinline__ unsigned cvt_pk_bf16(float lo, float hi) { unsigned r; asm volatile("v_cvt_pk_bf16_f32 %0, %1, %2" : "=v"(r) : "v"(lo), "v"(hi)); return r; }
; __device__ __forceinline__ void phase_attn_diff(const Params& p, char* lds) {
;     ...
;                     const float rs = rsqrtf(ss * (1.0f / 128.0f) + EPS);
;                     bf16_t* Or = Ow + (size_t)((r & 3) + 8 * (r >> 2)) * 1024;
;                     Or[0] = (bf16_t)(cvt_pk_bf16(v0 * rs * gs[0], 0.f) & 0xffffu); Or[32] = (bf16_t)(cvt_pk_bf16(v1 * rs * gs[1], 0.f) & 0xffffu);
;                     Or[64] = (bf16_t)(cvt_pk_bf16(v2 * rs * gs[2], 0.f) & 0xffffu); Or[96] = (bf16_t)(cvt_pk_bf16(v3 * rs * gs[3], 0.f) & 0xffffu);
	v_add_co_u32_e32 v2, vcc, s67, v30
	s_nop 1
	v_addc_co_u32_e32 v3, vcc, 0, v31, vcc
	v_add_co_u32_e32 v18, vcc, s55, v30
	s_nop 1
	v_addc_co_u32_e32 v19, vcc, 0, v31, vcc
	v_add_co_u32_e32 v34, vcc, s58, v30
	s_nop 1
	v_addc_co_u32_e32 v35, vcc, 0, v31, vcc
	v_add_co_u32_e32 v50, vcc, s2, v30
	s_nop 1
	v_addc_co_u32_e32 v51, vcc, 0, v31, vcc
	v_mul_f32_e32 v84, v84, v64
	v_mul_f32_e32 v85, v85, v64
	v_mul_f32_e32 v86, v86, v64
	v_mul_f32_e32 v87, v87, v64
	v_mul_f32_e32 v88, v88, v68
	v_mul_f32_e32 v89, v89, v68
	v_mul_f32_e32 v90, v90, v68
	v_mul_f32_e32 v91, v91, v68
	v_mul_f32_e32 v92, v92, v72
	v_mul_f32_e32 v93, v93, v72
	v_mul_f32_e32 v94, v94, v72
	v_mul_f32_e32 v95, v95, v72
	v_mul_f32_e32 v100, v100, v0
	v_mul_f32_e32 v101, v101, v0
	v_mul_f32_e32 v102, v102, v0
	v_mul_f32_e32 v103, v103, v0
	v_mul_f32_e32 v104, v104, v16
	v_mul_f32_e32 v105, v105, v16
	v_mul_f32_e32 v106, v106, v16
	v_mul_f32_e32 v107, v107, v16
	v_mul_f32_e32 v108, v108, v32
	v_mul_f32_e32 v109, v109, v32
	v_mul_f32_e32 v110, v110, v32
	v_mul_f32_e32 v111, v111, v32
	v_mul_f32_e32 v112, v112, v48
	v_mul_f32_e32 v113, v113, v48
	v_mul_f32_e32 v114, v114, v48
	v_mul_f32_e32 v115, v115, v48
	v_mul_f32_e32 v116, v116, v4
	v_mul_f32_e32 v117, v117, v4
	v_mul_f32_e32 v118, v118, v4
	v_mul_f32_e32 v119, v119, v4
	v_mul_f32_e32 v120, v120, v20
	v_mul_f32_e32 v121, v121, v20
	v_mul_f32_e32 v122, v122, v20
	v_mul_f32_e32 v123, v123, v20
	v_mul_f32_e32 v124, v124, v36
	v_mul_f32_e32 v125, v125, v36
	v_mul_f32_e32 v126, v126, v36
	v_mul_f32_e32 v127, v127, v36
	v_mul_f32_e32 v128, v128, v52
	v_mul_f32_e32 v129, v129, v52
	v_mul_f32_e32 v130, v130, v52
	v_mul_f32_e32 v131, v131, v52
	v_mul_f32_e32 v132, v132, v8
	v_mul_f32_e32 v133, v133, v8
	v_mul_f32_e32 v134, v134, v8
	v_mul_f32_e32 v135, v135, v8
	v_mul_f32_e32 v136, v136, v24
	v_mul_f32_e32 v137, v137, v24
	v_mul_f32_e32 v138, v138, v24
	v_mul_f32_e32 v139, v139, v24
	v_mul_f32_e32 v140, v140, v40
	v_mul_f32_e32 v141, v141, v40
	v_mul_f32_e32 v142, v142, v40
	v_mul_f32_e32 v143, v143, v40
	v_mul_f32_e32 v144, v144, v56
	v_mul_f32_e32 v145, v145, v56
	v_mul_f32_e32 v146, v146, v56
	v_mul_f32_e32 v147, v147, v56
	v_mul_f32_e32 v148, v148, v12
	v_mul_f32_e32 v149, v149, v12
	v_mul_f32_e32 v150, v150, v12
	v_mul_f32_e32 v151, v151, v12
	v_mul_f32_e32 v84, v172, v84
	v_mul_f32_e32 v85, v173, v85
	v_mul_f32_e32 v86, v174, v86
	v_mul_f32_e32 v87, v175, v87
	v_mul_f32_e32 v88, v172, v88
	v_mul_f32_e32 v89, v173, v89
	v_mul_f32_e32 v90, v174, v90
	v_mul_f32_e32 v91, v175, v91
	v_mul_f32_e32 v92, v172, v92
	v_mul_f32_e32 v93, v173, v93
	v_mul_f32_e32 v94, v174, v94
	v_mul_f32_e32 v95, v175, v95
	v_mul_f32_e32 v100, v172, v100
	v_mul_f32_e32 v101, v173, v101
	v_mul_f32_e32 v102, v174, v102
	v_mul_f32_e32 v103, v175, v103
	v_mul_f32_e32 v104, v172, v104
	v_mul_f32_e32 v105, v173, v105
	v_mul_f32_e32 v106, v174, v106
	v_mul_f32_e32 v107, v175, v107
	v_mul_f32_e32 v108, v172, v108
	v_mul_f32_e32 v109, v173, v109
	v_mul_f32_e32 v110, v174, v110
	v_mul_f32_e32 v111, v175, v111
	v_mul_f32_e32 v112, v172, v112
	v_mul_f32_e32 v113, v173, v113
	v_mul_f32_e32 v114, v174, v114
	v_mul_f32_e32 v115, v175, v115
	v_mul_f32_e32 v116, v172, v116
	v_mul_f32_e32 v117, v173, v117
	v_mul_f32_e32 v118, v174, v118
	v_mul_f32_e32 v119, v175, v119
	v_mul_f32_e32 v120, v172, v120
	v_mul_f32_e32 v121, v173, v121
	v_mul_f32_e32 v122, v174, v122
	v_mul_f32_e32 v123, v175, v123
	v_mul_f32_e32 v124, v172, v124
	v_mul_f32_e32 v125, v173, v125
	v_mul_f32_e32 v126, v174, v126
	v_mul_f32_e32 v127, v175, v127
	v_mul_f32_e32 v128, v172, v128
	v_mul_f32_e32 v129, v173, v129
	v_mul_f32_e32 v130, v174, v130
	v_mul_f32_e32 v131, v175, v131
	v_mul_f32_e32 v132, v172, v132
	v_mul_f32_e32 v133, v173, v133
	v_mul_f32_e32 v134, v174, v134
	v_mul_f32_e32 v135, v175, v135
	v_mul_f32_e32 v136, v172, v136
	v_mul_f32_e32 v137, v173, v137
	v_mul_f32_e32 v138, v174, v138
	v_mul_f32_e32 v139, v175, v139
	v_mul_f32_e32 v140, v172, v140
	v_mul_f32_e32 v141, v173, v141
	v_mul_f32_e32 v142, v174, v142
	v_mul_f32_e32 v143, v175, v143
	v_mul_f32_e32 v144, v172, v144
	v_mul_f32_e32 v145, v173, v145
	v_mul_f32_e32 v146, v174, v146
	v_mul_f32_e32 v147, v175, v147
	v_mul_f32_e32 v148, v172, v148
	v_mul_f32_e32 v149, v173, v149
	v_mul_f32_e32 v150, v174, v150
	v_mul_f32_e32 v151, v175, v151
	v_cvt_pk_bf16_f32 v84, v84, v97
	v_cvt_pk_bf16_f32 v85, v85, v97
	v_cvt_pk_bf16_f32 v86, v86, v97
	v_cvt_pk_bf16_f32 v87, v87, v97
	v_cvt_pk_bf16_f32 v88, v88, v97
	v_cvt_pk_bf16_f32 v89, v89, v97
	v_cvt_pk_bf16_f32 v90, v90, v97
	v_cvt_pk_bf16_f32 v91, v91, v97
	v_cvt_pk_bf16_f32 v92, v92, v97
	v_cvt_pk_bf16_f32 v93, v93, v97
	v_cvt_pk_bf16_f32 v94, v94, v97
	v_cvt_pk_bf16_f32 v95, v95, v97
	v_cvt_pk_bf16_f32 v100, v100, v97
	v_cvt_pk_bf16_f32 v101, v101, v97
	v_cvt_pk_bf16_f32 v102, v102, v97
	v_cvt_pk_bf16_f32 v103, v103, v97
	v_cvt_pk_bf16_f32 v104, v104, v97
; __device__ __forceinline__ unsigned cvt_pk_bf16(float lo, float hi) { unsigned r; asm volatile("v_cvt_pk_bf16_f32 %0, %1, %2" : "=v"(r) : "v"(lo), "v"(hi)); return r; }
; __device__ __forceinline__ void phase_attn_diff(const Params& p, char* lds) {
;     ...
;                     bf16_t* Or = Ow + (size_t)((r & 3) + 8 * (r >> 2)) * 1024;
;                     Or[0] = (bf16_t)(cvt_pk_bf16(v0 * rs * gs[0], 0.f) & 0xffffu); Or[32] = (bf16_t)(cvt_pk_bf16(v1 * rs * gs[1], 0.f) & 0xffffu);
;                     Or[64] = (bf16_t)(cvt_pk_bf16(v2 * rs * gs[2], 0.f) & 0xffffu); Or[96] = (bf16_t)(cvt_pk_bf16(v3 * rs * gs[3], 0.f) & 0xffffu);
	v_cvt_pk_bf16_f32 v105, v105, v97
	v_cvt_pk_bf16_f32 v106, v106, v97
	v_cvt_pk_bf16_f32 v107, v107, v97
	v_cvt_pk_bf16_f32 v108, v108, v97
	v_cvt_pk_bf16_f32 v109, v109, v97
	v_cvt_pk_bf16_f32 v110, v110, v97
	v_cvt_pk_bf16_f32 v111, v111, v97
	v_cvt_pk_bf16_f32 v112, v112, v97
	v_cvt_pk_bf16_f32 v113, v113, v97
	v_cvt_pk_bf16_f32 v114, v114, v97
	v_cvt_pk_bf16_f32 v115, v115, v97
	v_cvt_pk_bf16_f32 v116, v116, v97
	v_cvt_pk_bf16_f32 v117, v117, v97
	v_cvt_pk_bf16_f32 v118, v118, v97
	v_cvt_pk_bf16_f32 v119, v119, v97
	v_cvt_pk_bf16_f32 v120, v120, v97
	v_cvt_pk_bf16_f32 v121, v121, v97
	v_cvt_pk_bf16_f32 v122, v122, v97
	v_cvt_pk_bf16_f32 v123, v123, v97
	v_cvt_pk_bf16_f32 v124, v124, v97
	v_cvt_pk_bf16_f32 v125, v125, v97
	v_cvt_pk_bf16_f32 v126, v126, v97
	v_cvt_pk_bf16_f32 v127, v127, v97
	v_cvt_pk_bf16_f32 v128, v128, v97
	v_cvt_pk_bf16_f32 v129, v129, v97
	v_cvt_pk_bf16_f32 v130, v130, v97
	v_cvt_pk_bf16_f32 v131, v131, v97
	v_cvt_pk_bf16_f32 v132, v132, v97
	v_cvt_pk_bf16_f32 v133, v133, v97
	v_cvt_pk_bf16_f32 v134, v134, v97
	v_cvt_pk_bf16_f32 v135, v135, v97
	v_cvt_pk_bf16_f32 v136, v136, v97
	v_cvt_pk_bf16_f32 v137, v137, v97
	v_cvt_pk_bf16_f32 v138, v138, v97
	v_cvt_pk_bf16_f32 v139, v139, v97
	v_cvt_pk_bf16_f32 v140, v140, v97
	v_cvt_pk_bf16_f32 v141, v141, v97
	v_cvt_pk_bf16_f32 v142, v142, v97
	v_cvt_pk_bf16_f32 v143, v143, v97
	v_cvt_pk_bf16_f32 v144, v144, v97
	v_cvt_pk_bf16_f32 v145, v145, v97
	v_cvt_pk_bf16_f32 v146, v146, v97
	v_cvt_pk_bf16_f32 v147, v147, v97
	v_cvt_pk_bf16_f32 v148, v148, v97
	v_cvt_pk_bf16_f32 v149, v149, v97
	v_cvt_pk_bf16_f32 v150, v150, v97
	v_cvt_pk_bf16_f32 v151, v151, v97
	global_store_short v[30:31], v84, off
	global_store_short v[30:31], v85, off offset:64
	global_store_short v[30:31], v86, off offset:128
	global_store_short v[30:31], v87, off offset:192
	global_store_short v[30:31], v88, off offset:2048
	global_store_short v[30:31], v89, off offset:2112
	global_store_short v[30:31], v90, off offset:2176
	global_store_short v[30:31], v91, off offset:2240
	global_store_short v[66:67], v92, off
	global_store_short v[66:67], v93, off offset:64
	global_store_short v[66:67], v94, off offset:128
	global_store_short v[66:67], v95, off offset:192
	global_store_short v[66:67], v100, off offset:2048
	global_store_short v[66:67], v101, off offset:2112
	global_store_short v[66:67], v102, off offset:2176
	global_store_short v[66:67], v103, off offset:2240
	global_store_short v[70:71], v104, off
	global_store_short v[70:71], v105, off offset:64
	global_store_short v[70:71], v106, off offset:128
	global_store_short v[70:71], v107, off offset:192
	global_store_short v[70:71], v108, off offset:2048
	global_store_short v[70:71], v109, off offset:2112
	global_store_short v[70:71], v110, off offset:2176
	global_store_short v[70:71], v111, off offset:2240
	global_store_short v[74:75], v112, off
	global_store_short v[74:75], v113, off offset:64
	global_store_short v[74:75], v114, off offset:128
	global_store_short v[74:75], v115, off offset:192
	global_store_short v[74:75], v116, off offset:2048
	global_store_short v[74:75], v117, off offset:2112
	global_store_short v[74:75], v118, off offset:2176
	global_store_short v[74:75], v119, off offset:2240
	global_store_short v[2:3], v120, off
	global_store_short v[2:3], v121, off offset:64
	global_store_short v[2:3], v122, off offset:128
	global_store_short v[2:3], v123, off offset:192
	global_store_short v[2:3], v124, off offset:2048
	global_store_short v[2:3], v125, off offset:2112
	global_store_short v[2:3], v126, off offset:2176
	global_store_short v[2:3], v127, off offset:2240
	global_store_short v[18:19], v128, off
	global_store_short v[18:19], v129, off offset:64
	global_store_short v[18:19], v130, off offset:128
	global_store_short v[18:19], v131, off offset:192
	global_store_short v[18:19], v132, off offset:2048
	global_store_short v[18:19], v133, off offset:2112
	global_store_short v[18:19], v134, off offset:2176
	global_store_short v[18:19], v135, off offset:2240
	global_store_short v[34:35], v136, off
	global_store_short v[34:35], v137, off offset:64
	global_store_short v[34:35], v138, off offset:128
	global_store_short v[34:35], v139, off offset:192
	global_store_short v[34:35], v140, off offset:2048
	global_store_short v[34:35], v141, off offset:2112
	global_store_short v[34:35], v142, off offset:2176
	global_store_short v[34:35], v143, off offset:2240
	global_store_short v[50:51], v144, off
	global_store_short v[50:51], v145, off offset:64
	global_store_short v[50:51], v146, off offset:128
	global_store_short v[50:51], v147, off offset:192
	global_store_short v[50:51], v148, off offset:2048
	global_store_short v[50:51], v149, off offset:2112
	global_store_short v[50:51], v150, off offset:2176
	global_store_short v[50:51], v151, off offset:2240
	s_cbranch_execnz .LBB0_169
	s_branch .LBB0_192
